# attention fast loop rotated: per-tile barrier sits before the last 4 PV MFMAs (operands already in registers) so they cover the post-barrier K-fragment LDS latency
# baseline (speedup 1.0000x reference)
; __device__ __forceinline__ void finishSM_fix(f32x16& p0, f32x16& p1, float& l_lane, bf16x8& pa0, bf16x8& pa1, bf16x8& pa2, bf16x8& pa3) {
; #pragma unroll
;   for (int r = 0; r < 16; ++r) p1[r] = __builtin_amdgcn_exp2f(p1[r]);
;   float ps = 0;
; #pragma unroll
;   for (int r = 0; r < 16; ++r) ps += p0[r];
; #pragma unroll
;   for (int r = 0; r < 16; ++r) ps += p1[r];
;   l_lane += ps;
;     ...
;   PK4(p0, 0, pa0); PK4(p0, 8, pa1); PK4(p1, 0, pa2); PK4(p1, 8, pa3);
;     ...
; }
; __device__ __forceinline__ void qkt12(f32x16& p0, f32x16& p1, const char* Ks, const bf16x8 (&qr)[12], const int (&kb)[4]) {
;   p0 = f32x16{}; p1 = f32x16{};
;     ...
;   bf16x8 c0 = KLD(0, 0), c1 = KLD(0, 1);
; #pragma unroll
;   for (int d0 = 0; d0 < 12; ++d0) {
;     bf16x8 n0 = c0, n1 = c1;
;     if (d0 < 11) { n0 = KLD(d0 + 1, 0); n1 = KLD(d0 + 1, 1); }
;     __builtin_amdgcn_sched_group_barrier(0x100, 2, 0);
;     p0 = __builtin_amdgcn_mfma_f32_32x32x16_bf16(c0, qr[d0], p0, 0, 0, 0);
;     p1 = __builtin_amdgcn_mfma_f32_32x32x16_bf16(c1, qr[d0], p1, 0, 0, 0);
;     __builtin_amdgcn_sched_group_barrier(0x008, 2, 0);
;     c0 = n0; c1 = n1; }
;     ...
; }
.Lfa_entry:
	v_mov_b32_e32 v82, v195
	v_mov_b32_e32 v83, v216
	v_mov_b32_e32 v84, v213
	v_mov_b32_e32 v85, v215
	v_mov_b32_e32 v86, v197
	v_mov_b32_e32 v87, v214
	v_mov_b32_e32 v88, v196
	v_mov_b32_e32 v89, v212
	v_mov_b32_e32 v90, v191
	v_mov_b32_e32 v91, v193
	v_mov_b32_e32 v92, v189
	v_mov_b32_e32 v93, v192
	v_mov_b32_e32 v94, v188
	v_mov_b32_e32 v95, v190
	v_mov_b32_e32 v96, v187
	v_mov_b32_e32 v97, v194
	s_add_i32 s22, s26, 1
	s_cmp_lg_u32 s26, 2
	s_cselect_b32 s24, s22, 0
	s_add_i32 s22, s24, 1
	s_cmp_lg_u32 s24, 2
	s_cselect_b32 s25, s22, 0
	s_waitcnt vmcnt(5)
	s_barrier
	s_mul_i32 s6, s24, 0x6000
	s_mul_i32 s10, s26, 0x6000
	s_lshl_b32 s11, s25, 14
	s_add_i32 s10, s43, s10
	s_add_i32 s11, s52, s11
	v_add_u32_e32 v187, s6, v183
	v_add_u32_e32 v188, s6, v184
	v_add_u32_e32 v189, s6, v185
	v_add_u32_e32 v190, s6, v186
	v_lshl_add_u32 v191, s26, 14, v182
	ds_read_b128 v[172:175], v187
	ds_read_b128 v[176:179], v187 offset:12288
	ds_read_b128 v[200:203], v188
	ds_read_b128 v[204:207], v188 offset:12288
.Lfa_loop:
	v_add_f32_e32 v196, v82, v83
	v_cvt_pk_bf16_f32 v82, v82, v83
	v_add_f32_e32 v197, v84, v85
	v_exp_f32_e32 v66, v66
	v_exp_f32_e32 v67, v67
	v_cvt_pk_bf16_f32 v83, v84, v85
	v_add_f32_e32 v196, v86, v196
	v_add_f32_e32 v197, v87, v197
	s_waitcnt lgkmcnt(3)
	v_mfma_f32_32x32x16_bf16 v[98:113], v[172:175], v[116:119], 0
	v_exp_f32_e32 v68, v68
	v_exp_f32_e32 v69, v69
	s_waitcnt lgkmcnt(2)
	v_mfma_f32_32x32x16_bf16 v[212:227], v[176:179], v[116:119], 0
	ds_read_b128 v[172:175], v189
	ds_read_b128 v[176:179], v189 offset:12288
	v_cvt_pk_bf16_f32 v84, v86, v87
	v_add_f32_e32 v196, v88, v196
	v_add_f32_e32 v197, v89, v197
	v_exp_f32_e32 v70, v70
	s_waitcnt lgkmcnt(3)
	v_mfma_f32_32x32x16_bf16 v[98:113], v[200:203], v[120:123], v[98:113]
	s_mov_b32 m0, s10
	v_lshl_add_u64 v[192:193], v[166:167], 0, s[92:93]
	global_load_lds_dwordx4 v[192:193], off
	v_exp_f32_e32 v71, v71
	s_waitcnt lgkmcnt(2)
	v_mfma_f32_32x32x16_bf16 v[212:227], v[204:207], v[120:123], v[212:227]
	ds_read_b128 v[200:203], v190
	ds_read_b128 v[204:207], v190 offset:12288
	v_cvt_pk_bf16_f32 v85, v88, v89
	v_add_f32_e32 v196, v90, v196
	v_add_f32_e32 v197, v91, v197
	v_exp_f32_e32 v72, v72
	s_waitcnt lgkmcnt(3)
	v_mfma_f32_32x32x16_bf16 v[98:113], v[172:175], v[124:127], v[98:113]
	v_exp_f32_e32 v73, v73
	s_waitcnt lgkmcnt(2)
	v_mfma_f32_32x32x16_bf16 v[212:227], v[176:179], v[124:127], v[212:227]
	ds_read_b128 v[172:175], v187 offset:128
	ds_read_b128 v[176:179], v187 offset:12416
	v_cvt_pk_bf16_f32 v86, v90, v91
	v_add_f32_e32 v196, v92, v196
	v_add_f32_e32 v197, v93, v197
	v_exp_f32_e32 v74, v74
	s_waitcnt lgkmcnt(3)
	v_mfma_f32_32x32x16_bf16 v[98:113], v[200:203], v[128:131], v[98:113]
	s_add_i32 m0, s10, 0x400
	v_lshl_add_u64 v[192:193], v[168:169], 0, s[92:93]
	global_load_lds_dwordx4 v[192:193], off
	v_exp_f32_e32 v75, v75
	v_cvt_pk_bf16_f32 v87, v92, v93
	s_waitcnt lgkmcnt(2)
	v_mfma_f32_32x32x16_bf16 v[212:227], v[204:207], v[128:131], v[212:227]
	ds_read_b128 v[200:203], v188 offset:128
	ds_read_b128 v[204:207], v188 offset:12416
	v_add_f32_e32 v196, v94, v196
	v_add_f32_e32 v197, v95, v197
	v_exp_f32_e32 v76, v76
	s_waitcnt lgkmcnt(3)
	v_mfma_f32_32x32x16_bf16 v[98:113], v[172:175], v[132:135], v[98:113]
	v_exp_f32_e32 v77, v77
	v_cvt_pk_bf16_f32 v88, v94, v95
	s_waitcnt lgkmcnt(2)
	v_mfma_f32_32x32x16_bf16 v[212:227], v[176:179], v[132:135], v[212:227]
	ds_read_b128 v[172:175], v189 offset:128
	ds_read_b128 v[176:179], v189 offset:12416
	v_add_f32_e32 v196, v96, v196
	v_add_f32_e32 v197, v97, v197
	v_exp_f32_e32 v78, v78
	s_waitcnt lgkmcnt(3)
	v_mfma_f32_32x32x16_bf16 v[98:113], v[200:203], v[136:139], v[98:113]
	s_add_i32 m0, s10, 0x800
	v_lshl_add_u64 v[192:193], v[170:171], 0, s[92:93]
	global_load_lds_dwordx4 v[192:193], off
	v_exp_f32_e32 v79, v79
	v_cvt_pk_bf16_f32 v89, v96, v97
	s_waitcnt lgkmcnt(2)
	v_mfma_f32_32x32x16_bf16 v[212:227], v[204:207], v[136:139], v[212:227]
	ds_read_b128 v[200:203], v190 offset:128
	ds_read_b128 v[204:207], v190 offset:12416
	v_exp_f32_e32 v80, v80
	v_exp_f32_e32 v81, v81
	s_waitcnt lgkmcnt(3)
	v_mfma_f32_32x32x16_bf16 v[98:113], v[172:175], v[140:143], v[98:113]
	v_add_f32_e32 v196, v66, v196
	v_add_f32_e32 v197, v67, v197
	v_cvt_pk_bf16_f32 v66, v66, v67
	s_waitcnt lgkmcnt(2)
	v_mfma_f32_32x32x16_bf16 v[212:227], v[176:179], v[140:143], v[212:227]
	ds_read_b128 v[172:175], v187 offset:256
	ds_read_b128 v[176:179], v187 offset:12544
	v_permlane32_swap_b32_e32 v82, v84
	v_permlane32_swap_b32_e32 v83, v85
	v_permlane32_swap_b32_e32 v86, v88
	v_permlane32_swap_b32_e32 v87, v89
	s_waitcnt lgkmcnt(3)
	v_mfma_f32_32x32x16_bf16 v[98:113], v[200:203], v[144:147], v[98:113]
	s_mov_b64 s[22:23], 0x61e0c100
	s_mov_b32 m0, s11
	v_lshl_add_u64 v[192:193], v[164:165], 0, s[22:23]
	global_load_lds_dwordx4 v[192:193], off
	v_add_f32_e32 v196, v68, v196
	v_add_f32_e32 v197, v69, v197
	v_cvt_pk_bf16_f32 v67, v68, v69
	s_waitcnt lgkmcnt(2)
	v_mfma_f32_32x32x16_bf16 v[212:227], v[204:207], v[144:147], v[212:227]
	ds_read_b128 v[200:203], v188 offset:256
	ds_read_b128 v[204:207], v188 offset:12544
	v_add_f32_e32 v196, v70, v196
	v_add_f32_e32 v197, v71, v197
	v_cvt_pk_bf16_f32 v68, v70, v71
	v_add_f32_e32 v196, v72, v196
	s_waitcnt lgkmcnt(3)
	v_mfma_f32_32x32x16_bf16 v[98:113], v[172:175], v[152:155], v[98:113]
	ds_read_b64_tr_b16 v[228:229], v191 offset:0
	ds_read_b64_tr_b16 v[230:231], v191 offset:2048
	v_add_f32_e32 v197, v73, v197
	v_cvt_pk_bf16_f32 v69, v72, v73
	v_add_f32_e32 v196, v74, v196
	v_add_f32_e32 v197, v75, v197
	s_waitcnt lgkmcnt(4)
; #define SBAR() __builtin_amdgcn_sched_barrier(0)
; __device__ __forceinline__ void partialSM_fix(f32x16& p0, f32x16& p1) {
; #pragma unroll
;   for (int r = 0; r < 16; ++r) p0[r] = __builtin_amdgcn_exp2f(p0[r]);
; }
; template <int D0> __device__ __forceinline__ void pv_one(f32x16& od, int vb, bf16x8 pa0, bf16x8 pa1, bf16x8 pa2, bf16x8 pa3) {
;   const s16x4 l0 = tr_read<v_rd_off(D0, 0, 0)>(vb), h0 = tr_read<v_rd_off(D0, 0, 1)>(vb), l1 = tr_read<v_rd_off(D0, 1, 0)>(vb), h1 = tr_read<v_rd_off(D0, 1, 1)>(vb);
;   const s16x4 l2 = tr_read<v_rd_off(D0, 2, 0)>(vb), h2 = tr_read<v_rd_off(D0, 2, 1)>(vb), l3 = tr_read<v_rd_off(D0, 3, 0)>(vb), h3 = tr_read<v_rd_off(D0, 3, 1)>(vb);
;   asm volatile("s_waitcnt lgkmcnt(0)" ::: "memory"); SBAR();
;     ...
;   od = __builtin_amdgcn_mfma_f32_32x32x16_bf16(pa0, PK(l0, h0), od, 0, 0, 0);
;   od = __builtin_amdgcn_mfma_f32_32x32x16_bf16(pa1, PK(l1, h1), od, 0, 0, 0);
;   od = __builtin_amdgcn_mfma_f32_32x32x16_bf16(pa2, PK(l2, h2), od, 0, 0, 0);
;   od = __builtin_amdgcn_mfma_f32_32x32x16_bf16(pa3, PK(l3, h3), od, 0, 0, 0);
;     ...
; }
; __device__ __forceinline__ void pv_d0(f32x16 (&o)[4], int vb, bf16x8 pa0, bf16x8 pa1, bf16x8 pa2, bf16x8 pa3) {
;   pv_one<0>(o[0], vb, pa0, pa1, pa2, pa3); pv_one<1>(o[1], vb, pa0, pa1, pa2, pa3); pv_one<2>(o[2], vb, pa0, pa1, pa2, pa3); pv_one<3>(o[3], vb, pa0, pa1, pa2, pa3);
	v_mfma_f32_32x32x16_bf16 v[212:227], v[176:179], v[152:155], v[212:227]
	ds_read_b128 v[172:175], v189 offset:256
	ds_read_b128 v[176:179], v189 offset:12544
	ds_read_b64_tr_b16 v[232:233], v191 offset:4096
	ds_read_b64_tr_b16 v[234:235], v191 offset:6144
	v_cvt_pk_bf16_f32 v70, v74, v75
	v_add_f32_e32 v196, v76, v196
	v_add_f32_e32 v197, v77, v197
	s_waitcnt lgkmcnt(7)
	v_mfma_f32_32x32x16_bf16 v[98:113], v[200:203], v[148:151], v[98:113]
	ds_read_b64_tr_b16 v[236:237], v191 offset:8192
	ds_read_b64_tr_b16 v[238:239], v191 offset:10240
	s_mov_b64 s[22:23], 0x61e0c180
	s_add_i32 m0, s11, 0x400
	v_lshl_add_u64 v[192:193], v[164:165], 0, s[22:23]
	global_load_lds_dwordx4 v[192:193], off
	v_cvt_pk_bf16_f32 v71, v76, v77
	v_add_f32_e32 v196, v78, v196
	v_add_f32_e32 v197, v79, v197
	v_cvt_pk_bf16_f32 v72, v78, v79
	s_waitcnt lgkmcnt(8)
	v_mfma_f32_32x32x16_bf16 v[212:227], v[204:207], v[148:151], v[212:227]
	ds_read_b128 v[200:203], v190 offset:256
	ds_read_b128 v[204:207], v190 offset:12544
	ds_read_b64_tr_b16 v[240:241], v191 offset:12288
	ds_read_b64_tr_b16 v[242:243], v191 offset:14336
	v_add_f32_e32 v196, v80, v196
	v_add_f32_e32 v197, v81, v197
	v_cvt_pk_bf16_f32 v73, v80, v81
	s_waitcnt lgkmcnt(9)
	v_mfma_f32_32x32x16_bf16 v[98:113], v[172:175], v[160:163], v[98:113]
	ds_read_b64_tr_b16 v[246:247], v191 offset:512
	ds_read_b64_tr_b16 v[248:249], v191 offset:2560
	v_add_f32_e32 v196, v196, v197
	s_nop 0
	v_permlane32_swap_b32_e32 v66, v68
	v_permlane32_swap_b32_e32 v67, v69
	s_waitcnt lgkmcnt(10)
	v_mfma_f32_32x32x16_bf16 v[212:227], v[176:179], v[160:163], v[212:227]
	ds_read_b64_tr_b16 v[250:251], v191 offset:4608
	ds_read_b64_tr_b16 v[252:253], v191 offset:6656
	v_permlane32_swap_b32_e32 v70, v72
	v_permlane32_swap_b32_e32 v71, v73
	v_add_f32_e32 v114, v114, v196
	s_waitcnt lgkmcnt(7)
	v_mfma_f32_32x32x16_bf16 v[98:113], v[200:203], v[156:159], v[98:113]
	s_waitcnt lgkmcnt(6)
	v_mfma_f32_32x32x16_bf16 v[212:227], v[204:207], v[156:159], v[212:227]
	v_mfma_f32_32x32x16_bf16 v[2:17], v[82:85], v[228:231], v[2:17]
	ds_read_b64_tr_b16 v[228:229], v191 offset:8704
	ds_read_b64_tr_b16 v[230:231], v191 offset:10752
	v_mfma_f32_32x32x16_bf16 v[2:17], v[86:89], v[232:235], v[2:17]
	ds_read_b64_tr_b16 v[232:233], v191 offset:12800
	ds_read_b64_tr_b16 v[234:235], v191 offset:14848
	v_mfma_f32_32x32x16_bf16 v[2:17], v[66:69], v[236:239], v[2:17]
	ds_read_b64_tr_b16 v[236:237], v191 offset:1024
	ds_read_b64_tr_b16 v[238:239], v191 offset:3072
	s_waitcnt lgkmcnt(10)
	v_mfma_f32_32x32x16_bf16 v[2:17], v[70:73], v[240:243], v[2:17]
	ds_read_b64_tr_b16 v[240:241], v191 offset:5120
	ds_read_b64_tr_b16 v[242:243], v191 offset:7168
	v_exp_f32_e32 v98, v98
	s_waitcnt lgkmcnt(10)
	v_mfma_f32_32x32x16_bf16 v[18:33], v[82:85], v[246:249], v[18:33]
	ds_read_b64_tr_b16 v[246:247], v191 offset:9216
	ds_read_b64_tr_b16 v[248:249], v191 offset:11264
	v_exp_f32_e32 v99, v99
	s_waitcnt lgkmcnt(10)
	v_mfma_f32_32x32x16_bf16 v[18:33], v[86:89], v[250:253], v[18:33]
	ds_read_b64_tr_b16 v[250:251], v191 offset:13312
	ds_read_b64_tr_b16 v[252:253], v191 offset:15360
	v_exp_f32_e32 v100, v100
	s_waitcnt lgkmcnt(10)
	v_mfma_f32_32x32x16_bf16 v[18:33], v[66:69], v[228:231], v[18:33]
	ds_read_b64_tr_b16 v[228:229], v191 offset:1536
	ds_read_b64_tr_b16 v[230:231], v191 offset:3584
	v_exp_f32_e32 v101, v101
	s_waitcnt lgkmcnt(10)
	v_mfma_f32_32x32x16_bf16 v[18:33], v[70:73], v[232:235], v[18:33]
	ds_read_b64_tr_b16 v[232:233], v191 offset:5632
	ds_read_b64_tr_b16 v[234:235], v191 offset:7680
	v_exp_f32_e32 v102, v102
	s_waitcnt lgkmcnt(10)
	v_mfma_f32_32x32x16_bf16 v[34:49], v[82:85], v[236:239], v[34:49]
	ds_read_b64_tr_b16 v[236:237], v191 offset:9728
	ds_read_b64_tr_b16 v[238:239], v191 offset:11776
	v_exp_f32_e32 v103, v103
	s_waitcnt lgkmcnt(10)
	v_mfma_f32_32x32x16_bf16 v[34:49], v[86:89], v[240:243], v[34:49]
	ds_read_b64_tr_b16 v[240:241], v191 offset:13824
	ds_read_b64_tr_b16 v[242:243], v191 offset:15872
	v_exp_f32_e32 v104, v104
	s_waitcnt lgkmcnt(10)
	v_mfma_f32_32x32x16_bf16 v[34:49], v[66:69], v[246:249], v[34:49]
	v_exp_f32_e32 v105, v105
	s_waitcnt lgkmcnt(8)
	v_mfma_f32_32x32x16_bf16 v[34:49], v[70:73], v[250:253], v[34:49]
	v_exp_f32_e32 v106, v106
	s_waitcnt lgkmcnt(0)
	s_waitcnt vmcnt(5)
	s_barrier
; __device__ __forceinline__ void finishSM_fix(f32x16& p0, f32x16& p1, float& l_lane, bf16x8& pa0, bf16x8& pa1, bf16x8& pa2, bf16x8& pa3) {
; #pragma unroll
;   for (int r = 0; r < 16; ++r) p1[r] = __builtin_amdgcn_exp2f(p1[r]);
;   float ps = 0;
; #pragma unroll
;   for (int r = 0; r < 16; ++r) ps += p0[r];
; #pragma unroll
;   for (int r = 0; r < 16; ++r) ps += p1[r];
;   l_lane += ps;
;     ...
;   PK4(p0, 0, pa0); PK4(p0, 8, pa1); PK4(p1, 0, pa2); PK4(p1, 8, pa3);
;     ...
; }
; __device__ __forceinline__ void qkt12(f32x16& p0, f32x16& p1, const char* Ks, const bf16x8 (&qr)[12], const int (&kb)[4]) {
;   p0 = f32x16{}; p1 = f32x16{};
;     ...
;   bf16x8 c0 = KLD(0, 0), c1 = KLD(0, 1);
; #pragma unroll
;   for (int d0 = 0; d0 < 12; ++d0) {
;     bf16x8 n0 = c0, n1 = c1;
;     if (d0 < 11) { n0 = KLD(d0 + 1, 0); n1 = KLD(d0 + 1, 1); }
;     __builtin_amdgcn_sched_group_barrier(0x100, 2, 0);
;     p0 = __builtin_amdgcn_mfma_f32_32x32x16_bf16(c0, qr[d0], p0, 0, 0, 0);
;     p1 = __builtin_amdgcn_mfma_f32_32x32x16_bf16(c1, qr[d0], p1, 0, 0, 0);
;     __builtin_amdgcn_sched_group_barrier(0x008, 2, 0);
;     c0 = n0; c1 = n1; }
;     ...
; }
	s_mul_i32 s6, s25, 0x6000
	s_mul_i32 s10, s24, 0x6000
	s_lshl_b32 s11, s26, 14
	s_add_i32 s10, s43, s10
	s_add_i32 s11, s52, s11
	v_add_u32_e32 v187, s6, v183
	v_add_u32_e32 v188, s6, v184
	v_add_u32_e32 v189, s6, v185
	v_add_u32_e32 v190, s6, v186
	v_lshl_add_u32 v191, s24, 14, v182
	ds_read_b128 v[172:175], v187
	ds_read_b128 v[176:179], v187 offset:12288
	ds_read_b128 v[200:203], v188
	ds_read_b128 v[204:207], v188 offset:12288
	v_mfma_f32_32x32x16_bf16 v[50:65], v[82:85], v[228:231], v[50:65]
	v_exp_f32_e32 v107, v107
	v_exp_f32_e32 v108, v108
	v_mfma_f32_32x32x16_bf16 v[50:65], v[86:89], v[232:235], v[50:65]
	v_exp_f32_e32 v109, v109
	v_exp_f32_e32 v110, v110
	v_mfma_f32_32x32x16_bf16 v[50:65], v[66:69], v[236:239], v[50:65]
	v_exp_f32_e32 v111, v111
	v_exp_f32_e32 v112, v112
	v_mfma_f32_32x32x16_bf16 v[50:65], v[70:73], v[240:243], v[50:65]
	v_exp_f32_e32 v113, v113
	v_add_f32_e32 v196, v98, v99
	v_cvt_pk_bf16_f32 v98, v98, v99
	v_add_f32_e32 v197, v100, v101
	v_exp_f32_e32 v212, v212
	v_exp_f32_e32 v213, v213
	v_cvt_pk_bf16_f32 v99, v100, v101
	v_add_f32_e32 v196, v102, v196
	v_add_f32_e32 v197, v103, v197
	s_waitcnt lgkmcnt(3)
	v_mfma_f32_32x32x16_bf16 v[82:97], v[172:175], v[116:119], 0
	v_exp_f32_e32 v214, v214
	v_exp_f32_e32 v215, v215
	s_waitcnt lgkmcnt(2)
	v_mfma_f32_32x32x16_bf16 v[66:81], v[176:179], v[116:119], 0
	ds_read_b128 v[172:175], v189
	ds_read_b128 v[176:179], v189 offset:12288
	v_cvt_pk_bf16_f32 v100, v102, v103
	v_add_f32_e32 v196, v104, v196
	v_add_f32_e32 v197, v105, v197
	v_exp_f32_e32 v216, v216
	s_waitcnt lgkmcnt(3)
	v_mfma_f32_32x32x16_bf16 v[82:97], v[200:203], v[120:123], v[82:97]
	s_mov_b32 m0, s10
	v_lshl_add_u64 v[192:193], v[166:167], 0, s[94:95]
	global_load_lds_dwordx4 v[192:193], off
	v_exp_f32_e32 v217, v217
	s_waitcnt lgkmcnt(2)
	v_mfma_f32_32x32x16_bf16 v[66:81], v[204:207], v[120:123], v[66:81]
	ds_read_b128 v[200:203], v190
	ds_read_b128 v[204:207], v190 offset:12288
	v_cvt_pk_bf16_f32 v101, v104, v105
	v_add_f32_e32 v196, v106, v196
	v_add_f32_e32 v197, v107, v197
	v_exp_f32_e32 v218, v218
	s_waitcnt lgkmcnt(3)
	v_mfma_f32_32x32x16_bf16 v[82:97], v[172:175], v[124:127], v[82:97]
	v_exp_f32_e32 v219, v219
	s_waitcnt lgkmcnt(2)
	v_mfma_f32_32x32x16_bf16 v[66:81], v[176:179], v[124:127], v[66:81]
	ds_read_b128 v[172:175], v187 offset:128
	ds_read_b128 v[176:179], v187 offset:12416
	v_cvt_pk_bf16_f32 v102, v106, v107
	v_add_f32_e32 v196, v108, v196
	v_add_f32_e32 v197, v109, v197
	v_exp_f32_e32 v220, v220
	s_waitcnt lgkmcnt(3)
	v_mfma_f32_32x32x16_bf16 v[82:97], v[200:203], v[128:131], v[82:97]
	s_add_i32 m0, s10, 0x400
	v_lshl_add_u64 v[192:193], v[168:169], 0, s[94:95]
	global_load_lds_dwordx4 v[192:193], off
	v_exp_f32_e32 v221, v221
	v_cvt_pk_bf16_f32 v103, v108, v109
	s_waitcnt lgkmcnt(2)
	v_mfma_f32_32x32x16_bf16 v[66:81], v[204:207], v[128:131], v[66:81]
	ds_read_b128 v[200:203], v188 offset:128
	ds_read_b128 v[204:207], v188 offset:12416
	v_add_f32_e32 v196, v110, v196
	v_add_f32_e32 v197, v111, v197
	v_exp_f32_e32 v222, v222
	s_waitcnt lgkmcnt(3)
	v_mfma_f32_32x32x16_bf16 v[82:97], v[172:175], v[132:135], v[82:97]
	v_exp_f32_e32 v223, v223
	v_cvt_pk_bf16_f32 v104, v110, v111
	s_waitcnt lgkmcnt(2)
	v_mfma_f32_32x32x16_bf16 v[66:81], v[176:179], v[132:135], v[66:81]
	ds_read_b128 v[172:175], v189 offset:128
	ds_read_b128 v[176:179], v189 offset:12416
	v_add_f32_e32 v196, v112, v196
	v_add_f32_e32 v197, v113, v197
	v_exp_f32_e32 v224, v224
	s_waitcnt lgkmcnt(3)
	v_mfma_f32_32x32x16_bf16 v[82:97], v[200:203], v[136:139], v[82:97]
	s_add_i32 m0, s10, 0x800
	v_lshl_add_u64 v[192:193], v[170:171], 0, s[94:95]
	global_load_lds_dwordx4 v[192:193], off
	v_exp_f32_e32 v225, v225
	v_cvt_pk_bf16_f32 v105, v112, v113
	s_waitcnt lgkmcnt(2)
	v_mfma_f32_32x32x16_bf16 v[66:81], v[204:207], v[136:139], v[66:81]
	ds_read_b128 v[200:203], v190 offset:128
	ds_read_b128 v[204:207], v190 offset:12416
	v_exp_f32_e32 v226, v226
	v_exp_f32_e32 v227, v227
	s_waitcnt lgkmcnt(3)
	v_mfma_f32_32x32x16_bf16 v[82:97], v[172:175], v[140:143], v[82:97]
	v_add_f32_e32 v196, v212, v196
	v_add_f32_e32 v197, v213, v197
	v_cvt_pk_bf16_f32 v212, v212, v213
	s_waitcnt lgkmcnt(2)
	v_mfma_f32_32x32x16_bf16 v[66:81], v[176:179], v[140:143], v[66:81]
	ds_read_b128 v[172:175], v187 offset:256
	ds_read_b128 v[176:179], v187 offset:12544
	v_permlane32_swap_b32_e32 v98, v100
	v_permlane32_swap_b32_e32 v99, v101
	v_permlane32_swap_b32_e32 v102, v104
	v_permlane32_swap_b32_e32 v103, v105
	s_waitcnt lgkmcnt(3)
	v_mfma_f32_32x32x16_bf16 v[82:97], v[200:203], v[144:147], v[82:97]
	s_mov_b64 s[22:23], 0x61e8c100
	s_mov_b32 m0, s11
	v_lshl_add_u64 v[192:193], v[164:165], 0, s[22:23]
	global_load_lds_dwordx4 v[192:193], off
	v_add_f32_e32 v196, v214, v196
	v_add_f32_e32 v197, v215, v197
	v_cvt_pk_bf16_f32 v213, v214, v215
	s_waitcnt lgkmcnt(2)
	v_mfma_f32_32x32x16_bf16 v[66:81], v[204:207], v[144:147], v[66:81]
	ds_read_b128 v[200:203], v188 offset:256
	ds_read_b128 v[204:207], v188 offset:12544
	v_add_f32_e32 v196, v216, v196
	v_add_f32_e32 v197, v217, v197
	v_cvt_pk_bf16_f32 v214, v216, v217
	v_add_f32_e32 v196, v218, v196
	s_waitcnt lgkmcnt(3)
	v_mfma_f32_32x32x16_bf16 v[82:97], v[172:175], v[152:155], v[82:97]
	ds_read_b64_tr_b16 v[228:229], v191 offset:0
	ds_read_b64_tr_b16 v[230:231], v191 offset:2048
	v_add_f32_e32 v197, v219, v197
	v_cvt_pk_bf16_f32 v215, v218, v219
	v_add_f32_e32 v196, v220, v196
	v_add_f32_e32 v197, v221, v197
	s_waitcnt lgkmcnt(4)
; #define SBAR() __builtin_amdgcn_sched_barrier(0)
; #define TOP(t, st) do { if ((t) + 2 < NT) asm volatile("s_waitcnt vmcnt(5)" ::: "memory"); else asm volatile("s_waitcnt vmcnt(0)" ::: "memory"); \
;     __builtin_amdgcn_s_barrier(); asm volatile("" ::: "memory"); \
;     if ((t) + 2 < NT) KDMA((t) + 2, NEXT3(NEXT3(st))); if ((t) + 1 < NT) VDMA((t) + 1, NEXT3(st)); } while (0)
; template <int D0> __device__ __forceinline__ void pv_one(f32x16& od, int vb, bf16x8 pa0, bf16x8 pa1, bf16x8 pa2, bf16x8 pa3) {
;   const s16x4 l0 = tr_read<v_rd_off(D0, 0, 0)>(vb), h0 = tr_read<v_rd_off(D0, 0, 1)>(vb), l1 = tr_read<v_rd_off(D0, 1, 0)>(vb), h1 = tr_read<v_rd_off(D0, 1, 1)>(vb);
;   const s16x4 l2 = tr_read<v_rd_off(D0, 2, 0)>(vb), h2 = tr_read<v_rd_off(D0, 2, 1)>(vb), l3 = tr_read<v_rd_off(D0, 3, 0)>(vb), h3 = tr_read<v_rd_off(D0, 3, 1)>(vb);
;   asm volatile("s_waitcnt lgkmcnt(0)" ::: "memory"); SBAR();
;     ...
;   od = __builtin_amdgcn_mfma_f32_32x32x16_bf16(pa0, PK(l0, h0), od, 0, 0, 0);
;   od = __builtin_amdgcn_mfma_f32_32x32x16_bf16(pa1, PK(l1, h1), od, 0, 0, 0);
;   od = __builtin_amdgcn_mfma_f32_32x32x16_bf16(pa2, PK(l2, h2), od, 0, 0, 0);
;   od = __builtin_amdgcn_mfma_f32_32x32x16_bf16(pa3, PK(l3, h3), od, 0, 0, 0);
;     ...
; }
; __device__ __forceinline__ void pv_d0(f32x16 (&o)[4], int vb, bf16x8 pa0, bf16x8 pa1, bf16x8 pa2, bf16x8 pa3) {
;   pv_one<0>(o[0], vb, pa0, pa1, pa2, pa3); pv_one<1>(o[1], vb, pa0, pa1, pa2, pa3); pv_one<2>(o[2], vb, pa0, pa1, pa2, pa3); pv_one<3>(o[3], vb, pa0, pa1, pa2, pa3);
; __device__ __forceinline__ void attn_unit_dma(const bf16_t* __restrict__ Qb, const bf16_t* __restrict__ Kh, const bf16_t* __restrict__ Vh, int seq, char* lds, LAS unsigned char* ldsl, ...
;     ...
;   for (int j = 1; j + 1 < NT; j += 2) {
;     int sp = st; st = NEXT3(st);
;     TOP(j, st);
;     SBAR(); qkt12(pB0, pB1, lds + DMA_KRING + st * SHM_K, qr, kb);
;     finishSM_fix(pA0, pA1, l_reg, pa0, pa1, pa2, pa3); SBAR();
;     pv_d0(o, vb0 + sp * SHM_V, pa0, pa1, pa2, pa3); partialSM_fix(pB0, pB1);
;     sp = st; st = NEXT3(st);
;     TOP(j + 1, st);
;     SBAR(); qkt12(pA0, pA1, lds + DMA_KRING + st * SHM_K, qr, kb);
;     finishSM_fix(pB0, pB1, l_reg, pa0, pa1, pa2, pa3); SBAR();
;     pv_d0(o, vb0 + sp * SHM_V, pa0, pa1, pa2, pa3); partialSM_fix(pA0, pA1);
;   }
	v_mfma_f32_32x32x16_bf16 v[66:81], v[176:179], v[152:155], v[66:81]
	ds_read_b128 v[172:175], v189 offset:256
	ds_read_b128 v[176:179], v189 offset:12544
	ds_read_b64_tr_b16 v[232:233], v191 offset:4096
	ds_read_b64_tr_b16 v[234:235], v191 offset:6144
	v_cvt_pk_bf16_f32 v216, v220, v221
	v_add_f32_e32 v196, v222, v196
	v_add_f32_e32 v197, v223, v197
	s_waitcnt lgkmcnt(7)
	v_mfma_f32_32x32x16_bf16 v[82:97], v[200:203], v[148:151], v[82:97]
	ds_read_b64_tr_b16 v[236:237], v191 offset:8192
	ds_read_b64_tr_b16 v[238:239], v191 offset:10240
	s_mov_b64 s[22:23], 0x61e8c180
	s_add_i32 m0, s11, 0x400
	v_lshl_add_u64 v[192:193], v[164:165], 0, s[22:23]
	global_load_lds_dwordx4 v[192:193], off
	v_cvt_pk_bf16_f32 v217, v222, v223
	v_add_f32_e32 v196, v224, v196
	v_add_f32_e32 v197, v225, v197
	v_cvt_pk_bf16_f32 v218, v224, v225
	s_waitcnt lgkmcnt(8)
	v_mfma_f32_32x32x16_bf16 v[66:81], v[204:207], v[148:151], v[66:81]
	ds_read_b128 v[200:203], v190 offset:256
	ds_read_b128 v[204:207], v190 offset:12544
	ds_read_b64_tr_b16 v[240:241], v191 offset:12288
	ds_read_b64_tr_b16 v[242:243], v191 offset:14336
	v_add_f32_e32 v196, v226, v196
	v_add_f32_e32 v197, v227, v197
	v_cvt_pk_bf16_f32 v219, v226, v227
	s_waitcnt lgkmcnt(9)
	v_mfma_f32_32x32x16_bf16 v[82:97], v[172:175], v[160:163], v[82:97]
	ds_read_b64_tr_b16 v[246:247], v191 offset:512
	ds_read_b64_tr_b16 v[248:249], v191 offset:2560
	v_add_f32_e32 v196, v196, v197
	s_nop 0
	v_permlane32_swap_b32_e32 v212, v214
	v_permlane32_swap_b32_e32 v213, v215
	s_waitcnt lgkmcnt(10)
	v_mfma_f32_32x32x16_bf16 v[66:81], v[176:179], v[160:163], v[66:81]
	ds_read_b64_tr_b16 v[250:251], v191 offset:4608
	ds_read_b64_tr_b16 v[252:253], v191 offset:6656
	v_permlane32_swap_b32_e32 v216, v218
	v_permlane32_swap_b32_e32 v217, v219
	v_add_f32_e32 v114, v114, v196
	s_waitcnt lgkmcnt(7)
	v_mfma_f32_32x32x16_bf16 v[82:97], v[200:203], v[156:159], v[82:97]
	s_waitcnt lgkmcnt(6)
	v_mfma_f32_32x32x16_bf16 v[66:81], v[204:207], v[156:159], v[66:81]
	v_mfma_f32_32x32x16_bf16 v[2:17], v[98:101], v[228:231], v[2:17]
	ds_read_b64_tr_b16 v[228:229], v191 offset:8704
	ds_read_b64_tr_b16 v[230:231], v191 offset:10752
	v_mfma_f32_32x32x16_bf16 v[2:17], v[102:105], v[232:235], v[2:17]
	ds_read_b64_tr_b16 v[232:233], v191 offset:12800
	ds_read_b64_tr_b16 v[234:235], v191 offset:14848
	v_mfma_f32_32x32x16_bf16 v[2:17], v[212:215], v[236:239], v[2:17]
	ds_read_b64_tr_b16 v[236:237], v191 offset:1024
	ds_read_b64_tr_b16 v[238:239], v191 offset:3072
	v_lshl_add_u64 v[166:167], v[166:167], 0, s[90:91]
	s_waitcnt lgkmcnt(10)
	v_mfma_f32_32x32x16_bf16 v[2:17], v[216:219], v[240:243], v[2:17]
	ds_read_b64_tr_b16 v[240:241], v191 offset:5120
	ds_read_b64_tr_b16 v[242:243], v191 offset:7168
	v_exp_f32_e32 v82, v82
	v_lshl_add_u64 v[168:169], v[168:169], 0, s[90:91]
	s_waitcnt lgkmcnt(10)
	v_mfma_f32_32x32x16_bf16 v[18:33], v[98:101], v[246:249], v[18:33]
	ds_read_b64_tr_b16 v[246:247], v191 offset:9216
	ds_read_b64_tr_b16 v[248:249], v191 offset:11264
	v_exp_f32_e32 v83, v83
	v_lshl_add_u64 v[170:171], v[170:171], 0, s[90:91]
	s_waitcnt lgkmcnt(10)
	v_mfma_f32_32x32x16_bf16 v[18:33], v[102:105], v[250:253], v[18:33]
	ds_read_b64_tr_b16 v[250:251], v191 offset:13312
	ds_read_b64_tr_b16 v[252:253], v191 offset:15360
	v_exp_f32_e32 v84, v84
	v_lshl_add_u64 v[164:165], v[164:165], 0, s[68:69]
	s_waitcnt lgkmcnt(10)
	v_mfma_f32_32x32x16_bf16 v[18:33], v[212:215], v[228:231], v[18:33]
	ds_read_b64_tr_b16 v[228:229], v191 offset:1536
	ds_read_b64_tr_b16 v[230:231], v191 offset:3584
	v_exp_f32_e32 v85, v85
	s_waitcnt lgkmcnt(10)
	v_mfma_f32_32x32x16_bf16 v[18:33], v[216:219], v[232:235], v[18:33]
	ds_read_b64_tr_b16 v[232:233], v191 offset:5632
	ds_read_b64_tr_b16 v[234:235], v191 offset:7680
	v_exp_f32_e32 v86, v86
	s_waitcnt lgkmcnt(10)
	v_mfma_f32_32x32x16_bf16 v[34:49], v[98:101], v[236:239], v[34:49]
	ds_read_b64_tr_b16 v[236:237], v191 offset:9728
	ds_read_b64_tr_b16 v[238:239], v191 offset:11776
	v_exp_f32_e32 v87, v87
	s_waitcnt lgkmcnt(10)
	v_mfma_f32_32x32x16_bf16 v[34:49], v[102:105], v[240:243], v[34:49]
	ds_read_b64_tr_b16 v[240:241], v191 offset:13824
	ds_read_b64_tr_b16 v[242:243], v191 offset:15872
	v_exp_f32_e32 v88, v88
	s_waitcnt lgkmcnt(10)
	v_mfma_f32_32x32x16_bf16 v[34:49], v[212:215], v[246:249], v[34:49]
	v_exp_f32_e32 v89, v89
	s_waitcnt lgkmcnt(8)
	v_mfma_f32_32x32x16_bf16 v[34:49], v[216:219], v[250:253], v[34:49]
	v_exp_f32_e32 v90, v90
	s_mov_b32 s26, s25
	s_add_i32 s72, s72, 2
	s_cmp_lt_u32 s72, s37
	s_cbranch_scc0 .Lfa_fin
	s_waitcnt lgkmcnt(0)
	s_add_i32 s22, s26, 1
	s_cmp_lg_u32 s26, 2
	s_cselect_b32 s24, s22, 0
	s_add_i32 s22, s24, 1
	s_cmp_lg_u32 s24, 2
	s_cselect_b32 s25, s22, 0
	s_waitcnt vmcnt(5)
	s_barrier
	s_mul_i32 s6, s24, 0x6000
	s_mul_i32 s10, s26, 0x6000
	s_lshl_b32 s11, s25, 14
	s_add_i32 s10, s43, s10
	s_add_i32 s11, s52, s11
	v_add_u32_e32 v187, s6, v183
	v_add_u32_e32 v188, s6, v184
	v_add_u32_e32 v189, s6, v185
	v_add_u32_e32 v190, s6, v186
	v_lshl_add_u32 v191, s26, 14, v182
	ds_read_b128 v[172:175], v187
	ds_read_b128 v[176:179], v187 offset:12288
	ds_read_b128 v[200:203], v188
	ds_read_b128 v[204:207], v188 offset:12288
	v_mfma_f32_32x32x16_bf16 v[50:65], v[98:101], v[228:231], v[50:65]
	v_exp_f32_e32 v91, v91
	v_exp_f32_e32 v92, v92
	v_mfma_f32_32x32x16_bf16 v[50:65], v[102:105], v[232:235], v[50:65]
	v_exp_f32_e32 v93, v93
	v_exp_f32_e32 v94, v94
	v_mfma_f32_32x32x16_bf16 v[50:65], v[212:215], v[236:239], v[50:65]
	v_exp_f32_e32 v95, v95
	v_exp_f32_e32 v96, v96
	v_mfma_f32_32x32x16_bf16 v[50:65], v[216:219], v[240:243], v[50:65]
	v_exp_f32_e32 v97, v97
	s_branch .Lfa_loop
.Lfa_fin:
	s_waitcnt lgkmcnt(6)
	v_mfma_f32_32x32x16_bf16 v[50:65], v[98:101], v[228:231], v[50:65]
	v_exp_f32_e32 v91, v91
	v_exp_f32_e32 v92, v92
	s_waitcnt lgkmcnt(4)
	v_mfma_f32_32x32x16_bf16 v[50:65], v[102:105], v[232:235], v[50:65]
	v_exp_f32_e32 v93, v93
	v_exp_f32_e32 v94, v94
	s_waitcnt lgkmcnt(2)
	v_mfma_f32_32x32x16_bf16 v[50:65], v[212:215], v[236:239], v[50:65]
	v_exp_f32_e32 v95, v95
	v_exp_f32_e32 v96, v96
	s_waitcnt lgkmcnt(0)
	v_mfma_f32_32x32x16_bf16 v[50:65], v[216:219], v[240:243], v[50:65]
	v_exp_f32_e32 v97, v97
	v_mov_b32_e32 v195, v82
	v_mov_b32_e32 v216, v83
	v_mov_b32_e32 v213, v84
	v_mov_b32_e32 v215, v85
	v_mov_b32_e32 v197, v86
	v_mov_b32_e32 v214, v87
	v_mov_b32_e32 v196, v88
	v_mov_b32_e32 v212, v89
	v_mov_b32_e32 v191, v90
	v_mov_b32_e32 v193, v91
	v_mov_b32_e32 v189, v92
	v_mov_b32_e32 v192, v93
	v_mov_b32_e32 v188, v94
	v_mov_b32_e32 v190, v95
	v_mov_b32_e32 v187, v96
	v_mov_b32_e32 v194, v97
	s_branch .LBB0_853
	s_nop 0
	s_nop 0
	s_nop 0
	s_nop 0
	s_nop 0
	s_nop 0
	s_nop 0
	s_nop 0
